# combined: gm epilogue gate batching + mout epilogue second-half preloads, with alignment padding so hot loops keep v50 layout
# speedup vs baseline: 1.0062x; 1.0053x over previous
.LBB0_770:
	v_mov_b32_e32 v128, v182
	s_mov_b64 s[2:3], s[16:17]
	v_and_b32_e32 v128, 63, v128
	s_add_u32 s30, s30, s22
	v_ashrrev_i32_e32 v129, 31, v128
	s_addc_u32 s31, s31, s23
	v_lshl_add_u64 v[156:157], v[128:129], 4, s[2:3]
	v_lshl_add_u64 v[158:159], v[156:157], 0, s[4:5]
	v_lshl_add_u64 v[156:157], v[156:157], 0, s[30:31]
	s_mov_b64 s[98:99], 0x1000
	v_mov_b64_e32 v[248:249], v[158:159]
	v_mov_b64_e32 v[250:251], v[156:157]
	global_load_dwordx4 v[184:187], v[248:249], off nt
	global_load_dwordx4 v[188:191], v[250:251], off
	global_load_dwordx4 v[192:195], v[248:249], off offset:1024 nt
	global_load_dwordx4 v[196:199], v[250:251], off offset:1024
	global_load_dwordx4 v[200:203], v[248:249], off offset:2048 nt
	global_load_dwordx4 v[204:207], v[250:251], off offset:2048
	global_load_dwordx4 v[208:211], v[248:249], off offset:3072 nt
	global_load_dwordx4 v[212:215], v[250:251], off offset:3072
	v_lshl_add_u64 v[248:249], v[248:249], 0, s[98:99]
	v_lshl_add_u64 v[250:251], v[250:251], 0, s[98:99]
	global_load_dwordx4 v[216:219], v[248:249], off nt
	global_load_dwordx4 v[220:223], v[250:251], off
	global_load_dwordx4 v[224:227], v[248:249], off offset:1024 nt
	global_load_dwordx4 v[228:231], v[250:251], off offset:1024
	global_load_dwordx4 v[232:235], v[248:249], off offset:2048 nt
	global_load_dwordx4 v[236:239], v[250:251], off offset:2048
	global_load_dwordx4 v[240:243], v[248:249], off offset:3072 nt
	global_load_dwordx4 v[244:247], v[250:251], off offset:3072
	v_lshl_add_u64 v[248:249], v[248:249], 0, s[98:99]
	v_lshl_add_u64 v[250:251], v[250:251], 0, s[98:99]
	s_waitcnt vmcnt(14)
	v_mov_b64_e32 v[128:129], v[184:185]
	v_mov_b64_e32 v[130:131], v[186:187]
	v_mov_b64_e32 v[160:161], v[188:189]
	v_mov_b64_e32 v[162:163], v[190:191]
	global_load_dwordx4 v[184:187], v[248:249], off nt
	global_load_dwordx4 v[188:191], v[250:251], off
	v_lshlrev_b32_e32 v172, 16, v128
	v_lshlrev_b32_e32 v136, 16, v160
	v_and_b32_e32 v173, 0xffff0000, v128
	v_lshlrev_b32_e32 v128, 16, v161
	v_rcp_f32_e32 v170, v136
	v_and_b32_e32 v136, 0xffff0000, v160
	v_rcp_f32_e32 v160, v128
	v_and_b32_e32 v128, 0xffff0000, v161
	v_rcp_f32_e32 v161, v128
	v_lshlrev_b32_e32 v128, 16, v129
	v_and_b32_e32 v129, 0xffff0000, v129
	v_rcp_f32_e32 v171, v136
	v_pk_mul_f32 v[128:129], v[160:161], v[128:129]
	v_lshlrev_b32_e32 v160, 16, v130
	v_pk_mul_f32 v[10:11], v[10:11], v[128:129]
	v_lshlrev_b32_e32 v128, 16, v162
	v_and_b32_e32 v129, 0xffff0000, v162
	v_rcp_f32_e32 v128, v128
	v_rcp_f32_e32 v129, v129
	v_and_b32_e32 v161, 0xffff0000, v130
	v_lshlrev_b32_e32 v130, 16, v131
	v_and_b32_e32 v131, 0xffff0000, v131
	v_pk_mul_f32 v[128:129], v[128:129], v[160:161]
	v_pk_mul_f32 v[170:171], v[170:171], v[172:173]
	v_pk_mul_f32 v[12:13], v[12:13], v[128:129]
	v_lshlrev_b32_e32 v128, 16, v163
	v_and_b32_e32 v129, 0xffff0000, v163
	v_rcp_f32_e32 v128, v128
	v_rcp_f32_e32 v129, v129
	v_pk_mul_f32 v[8:9], v[8:9], v[170:171]
	v_pk_mul_f32 v[128:129], v[128:129], v[130:131]
	s_nop 0
	v_pk_mul_f32 v[14:15], v[14:15], v[128:129]
	s_waitcnt vmcnt(14)
	v_mov_b64_e32 v[128:129], v[192:193]
	v_mov_b64_e32 v[130:131], v[194:195]
	v_mov_b64_e32 v[160:161], v[196:197]
	v_mov_b64_e32 v[162:163], v[198:199]
	global_load_dwordx4 v[192:195], v[248:249], off offset:1024 nt
	global_load_dwordx4 v[196:199], v[250:251], off offset:1024
	v_lshlrev_b32_e32 v172, 16, v128
	v_lshlrev_b32_e32 v136, 16, v160
	v_and_b32_e32 v173, 0xffff0000, v128
	v_lshlrev_b32_e32 v128, 16, v161
	v_rcp_f32_e32 v170, v136
	v_and_b32_e32 v136, 0xffff0000, v160
	v_rcp_f32_e32 v160, v128
	v_and_b32_e32 v128, 0xffff0000, v161
	v_rcp_f32_e32 v161, v128
	v_lshlrev_b32_e32 v128, 16, v129
	v_and_b32_e32 v129, 0xffff0000, v129
	v_rcp_f32_e32 v171, v136
	v_pk_mul_f32 v[128:129], v[160:161], v[128:129]
	v_lshlrev_b32_e32 v160, 16, v130
	v_pk_mul_f32 v[30:31], v[30:31], v[128:129]
	v_lshlrev_b32_e32 v128, 16, v162
	v_and_b32_e32 v129, 0xffff0000, v162
	v_rcp_f32_e32 v128, v128
	v_rcp_f32_e32 v129, v129
	v_and_b32_e32 v161, 0xffff0000, v130
	v_lshlrev_b32_e32 v130, 16, v131
	v_and_b32_e32 v131, 0xffff0000, v131
	v_pk_mul_f32 v[128:129], v[128:129], v[160:161]
	v_pk_mul_f32 v[170:171], v[170:171], v[172:173]
	v_pk_mul_f32 v[32:33], v[32:33], v[128:129]
	v_lshlrev_b32_e32 v128, 16, v163
	v_and_b32_e32 v129, 0xffff0000, v163
	v_rcp_f32_e32 v128, v128
	v_rcp_f32_e32 v129, v129
	v_pk_mul_f32 v[28:29], v[28:29], v[170:171]
	v_pk_mul_f32 v[128:129], v[128:129], v[130:131]
	s_nop 0
	v_pk_mul_f32 v[34:35], v[34:35], v[128:129]
	s_nop 0
	s_waitcnt vmcnt(14)
	v_mov_b64_e32 v[128:129], v[200:201]
	v_mov_b64_e32 v[130:131], v[202:203]
	v_mov_b64_e32 v[160:161], v[204:205]
	v_mov_b64_e32 v[162:163], v[206:207]
	global_load_dwordx4 v[200:203], v[248:249], off offset:2048 nt
	global_load_dwordx4 v[204:207], v[250:251], off offset:2048
	v_lshlrev_b32_e32 v172, 16, v128
	v_lshlrev_b32_e32 v136, 16, v160
	v_and_b32_e32 v173, 0xffff0000, v128
	v_lshlrev_b32_e32 v128, 16, v161
	v_rcp_f32_e32 v170, v136
	v_and_b32_e32 v136, 0xffff0000, v160
	v_rcp_f32_e32 v160, v128
	v_and_b32_e32 v128, 0xffff0000, v161
	v_rcp_f32_e32 v161, v128
	v_lshlrev_b32_e32 v128, 16, v129
	v_and_b32_e32 v129, 0xffff0000, v129
	v_rcp_f32_e32 v171, v136
	v_pk_mul_f32 v[128:129], v[160:161], v[128:129]
	v_lshlrev_b32_e32 v160, 16, v130
	v_pk_mul_f32 v[42:43], v[42:43], v[128:129]
	v_lshlrev_b32_e32 v128, 16, v162
	v_and_b32_e32 v129, 0xffff0000, v162
	v_rcp_f32_e32 v128, v128
	v_rcp_f32_e32 v129, v129
	v_and_b32_e32 v161, 0xffff0000, v130
	v_lshlrev_b32_e32 v130, 16, v131
	v_and_b32_e32 v131, 0xffff0000, v131
	v_pk_mul_f32 v[128:129], v[128:129], v[160:161]
	v_pk_mul_f32 v[170:171], v[170:171], v[172:173]
	v_pk_mul_f32 v[44:45], v[44:45], v[128:129]
	v_lshlrev_b32_e32 v128, 16, v163
	v_and_b32_e32 v129, 0xffff0000, v163
	v_rcp_f32_e32 v128, v128
	v_rcp_f32_e32 v129, v129
	v_pk_mul_f32 v[40:41], v[40:41], v[170:171]
	v_pk_mul_f32 v[128:129], v[128:129], v[130:131]
	s_nop 0
	v_pk_mul_f32 v[46:47], v[46:47], v[128:129]
	s_waitcnt vmcnt(14)
	v_mov_b64_e32 v[128:129], v[208:209]
	v_mov_b64_e32 v[130:131], v[210:211]
	v_mov_b64_e32 v[160:161], v[212:213]
	v_mov_b64_e32 v[162:163], v[214:215]
	global_load_dwordx4 v[208:211], v[248:249], off offset:3072 nt
	global_load_dwordx4 v[212:215], v[250:251], off offset:3072
	v_lshl_add_u64 v[248:249], v[248:249], 0, s[98:99]
	v_lshl_add_u64 v[250:251], v[250:251], 0, s[98:99]
	v_lshlrev_b32_e32 v172, 16, v128
	v_lshlrev_b32_e32 v136, 16, v160
	v_and_b32_e32 v173, 0xffff0000, v128
	v_lshlrev_b32_e32 v128, 16, v161
	v_rcp_f32_e32 v170, v136
	v_and_b32_e32 v136, 0xffff0000, v160
	v_rcp_f32_e32 v160, v128
	v_and_b32_e32 v128, 0xffff0000, v161
	v_rcp_f32_e32 v161, v128
	v_lshlrev_b32_e32 v128, 16, v129
	v_and_b32_e32 v129, 0xffff0000, v129
	v_rcp_f32_e32 v171, v136
	v_pk_mul_f32 v[128:129], v[160:161], v[128:129]
	v_lshlrev_b32_e32 v160, 16, v130
	v_pk_mul_f32 v[50:51], v[50:51], v[128:129]
	v_lshlrev_b32_e32 v128, 16, v162
	v_and_b32_e32 v129, 0xffff0000, v162
	v_rcp_f32_e32 v128, v128
	v_rcp_f32_e32 v129, v129
	v_and_b32_e32 v161, 0xffff0000, v130
	v_lshlrev_b32_e32 v130, 16, v131
	v_and_b32_e32 v131, 0xffff0000, v131
	v_pk_mul_f32 v[128:129], v[128:129], v[160:161]
	v_add_co_u32_e32 v160, vcc, s82, v158
	v_pk_mul_f32 v[52:53], v[52:53], v[128:129]
	v_lshlrev_b32_e32 v128, 16, v163
	v_and_b32_e32 v129, 0xffff0000, v163
	v_rcp_f32_e32 v128, v128
	v_rcp_f32_e32 v129, v129
	v_pk_mul_f32 v[170:171], v[170:171], v[172:173]
	v_addc_co_u32_e32 v161, vcc, 0, v159, vcc
	v_pk_mul_f32 v[128:129], v[128:129], v[130:131]
	v_pk_mul_f32 v[48:49], v[48:49], v[170:171]
	v_pk_mul_f32 v[54:55], v[54:55], v[128:129]
	v_add_co_u32_e32 v162, vcc, s82, v156
	s_waitcnt vmcnt(14)
	v_mov_b64_e32 v[128:129], v[216:217]
	v_mov_b64_e32 v[130:131], v[218:219]
	s_nop 0
	v_addc_co_u32_e32 v163, vcc, 0, v157, vcc
	v_mov_b64_e32 v[170:171], v[220:221]
	v_mov_b64_e32 v[172:173], v[222:223]
	global_load_dwordx4 v[216:219], v[248:249], off nt
	global_load_dwordx4 v[220:223], v[250:251], off
	v_lshlrev_b32_e32 v176, 16, v128
	v_and_b32_e32 v177, 0xffff0000, v128
	v_lshlrev_b32_e32 v136, 16, v170
	v_lshlrev_b32_e32 v128, 16, v171
	v_rcp_f32_e32 v174, v136
	v_and_b32_e32 v136, 0xffff0000, v170
	v_rcp_f32_e32 v170, v128
	v_and_b32_e32 v128, 0xffff0000, v171
	v_rcp_f32_e32 v171, v128
	v_lshlrev_b32_e32 v128, 16, v129
	v_and_b32_e32 v129, 0xffff0000, v129
	v_rcp_f32_e32 v175, v136
	v_pk_mul_f32 v[128:129], v[170:171], v[128:129]
	v_lshlrev_b32_e32 v170, 16, v130
	v_pk_mul_f32 v[66:67], v[66:67], v[128:129]
	v_lshlrev_b32_e32 v128, 16, v172
	v_and_b32_e32 v129, 0xffff0000, v172
	v_rcp_f32_e32 v128, v128
	v_rcp_f32_e32 v129, v129
	v_and_b32_e32 v171, 0xffff0000, v130
	v_lshlrev_b32_e32 v130, 16, v131
	v_and_b32_e32 v131, 0xffff0000, v131
	v_pk_mul_f32 v[128:129], v[128:129], v[170:171]
	v_pk_mul_f32 v[174:175], v[174:175], v[176:177]
	v_pk_mul_f32 v[68:69], v[68:69], v[128:129]
	v_lshlrev_b32_e32 v128, 16, v173
	v_and_b32_e32 v129, 0xffff0000, v173
	v_rcp_f32_e32 v128, v128
	v_rcp_f32_e32 v129, v129
	v_pk_mul_f32 v[64:65], v[64:65], v[174:175]
	v_pk_mul_f32 v[128:129], v[128:129], v[130:131]
	s_nop 0
	v_pk_mul_f32 v[70:71], v[70:71], v[128:129]
	s_waitcnt vmcnt(14)
	v_mov_b64_e32 v[128:129], v[224:225]
	v_mov_b64_e32 v[130:131], v[226:227]
	v_mov_b64_e32 v[170:171], v[228:229]
	v_mov_b64_e32 v[172:173], v[230:231]
	global_load_dwordx4 v[224:227], v[248:249], off offset:1024 nt
	global_load_dwordx4 v[228:231], v[250:251], off offset:1024
	v_lshlrev_b32_e32 v176, 16, v128
	v_lshlrev_b32_e32 v136, 16, v170
	v_and_b32_e32 v177, 0xffff0000, v128
	v_lshlrev_b32_e32 v128, 16, v171
	v_rcp_f32_e32 v174, v136
	v_and_b32_e32 v136, 0xffff0000, v170
	v_rcp_f32_e32 v170, v128
	v_and_b32_e32 v128, 0xffff0000, v171
	v_rcp_f32_e32 v171, v128
	v_lshlrev_b32_e32 v128, 16, v129
	v_and_b32_e32 v129, 0xffff0000, v129
	v_rcp_f32_e32 v175, v136
	v_pk_mul_f32 v[128:129], v[170:171], v[128:129]
	v_lshlrev_b32_e32 v170, 16, v130
	v_pk_mul_f32 v[82:83], v[82:83], v[128:129]
	v_lshlrev_b32_e32 v128, 16, v172
	v_and_b32_e32 v129, 0xffff0000, v172
	v_rcp_f32_e32 v128, v128
	v_rcp_f32_e32 v129, v129
	v_and_b32_e32 v171, 0xffff0000, v130
	v_lshlrev_b32_e32 v130, 16, v131
	v_and_b32_e32 v131, 0xffff0000, v131
	v_pk_mul_f32 v[128:129], v[128:129], v[170:171]
	v_pk_mul_f32 v[174:175], v[174:175], v[176:177]
	v_pk_mul_f32 v[84:85], v[84:85], v[128:129]
	v_lshlrev_b32_e32 v128, 16, v173
	v_and_b32_e32 v129, 0xffff0000, v173
	v_rcp_f32_e32 v128, v128
	v_rcp_f32_e32 v129, v129
	v_pk_mul_f32 v[80:81], v[80:81], v[174:175]
	v_pk_mul_f32 v[128:129], v[128:129], v[130:131]
	s_nop 0
	v_pk_mul_f32 v[86:87], v[86:87], v[128:129]
	s_nop 0
	s_waitcnt vmcnt(14)
	v_mov_b64_e32 v[128:129], v[232:233]
	v_mov_b64_e32 v[130:131], v[234:235]
	v_mov_b64_e32 v[170:171], v[236:237]
	v_mov_b64_e32 v[172:173], v[238:239]
	global_load_dwordx4 v[232:235], v[248:249], off offset:2048 nt
	global_load_dwordx4 v[236:239], v[250:251], off offset:2048
	v_lshlrev_b32_e32 v176, 16, v128
	v_lshlrev_b32_e32 v136, 16, v170
	v_and_b32_e32 v177, 0xffff0000, v128
	v_lshlrev_b32_e32 v128, 16, v171
	v_rcp_f32_e32 v174, v136
	v_and_b32_e32 v136, 0xffff0000, v170
	v_rcp_f32_e32 v170, v128
	v_and_b32_e32 v128, 0xffff0000, v171
	v_rcp_f32_e32 v171, v128
	v_lshlrev_b32_e32 v128, 16, v129
	v_and_b32_e32 v129, 0xffff0000, v129
	v_rcp_f32_e32 v175, v136
	v_pk_mul_f32 v[128:129], v[170:171], v[128:129]
	v_lshlrev_b32_e32 v170, 16, v130
	v_pk_mul_f32 v[102:103], v[102:103], v[128:129]
	v_lshlrev_b32_e32 v128, 16, v172
	v_and_b32_e32 v129, 0xffff0000, v172
	v_rcp_f32_e32 v128, v128
	v_rcp_f32_e32 v129, v129
	v_and_b32_e32 v171, 0xffff0000, v130
	v_lshlrev_b32_e32 v130, 16, v131
	v_and_b32_e32 v131, 0xffff0000, v131
	v_pk_mul_f32 v[128:129], v[128:129], v[170:171]
	v_pk_mul_f32 v[174:175], v[174:175], v[176:177]
	v_pk_mul_f32 v[104:105], v[104:105], v[128:129]
	v_lshlrev_b32_e32 v128, 16, v173
	v_and_b32_e32 v129, 0xffff0000, v173
	v_rcp_f32_e32 v128, v128
	v_rcp_f32_e32 v129, v129
	v_pk_mul_f32 v[100:101], v[100:101], v[174:175]
	v_pk_mul_f32 v[128:129], v[128:129], v[130:131]
	s_nop 0
	v_pk_mul_f32 v[106:107], v[106:107], v[128:129]
	s_waitcnt vmcnt(14)
	v_mov_b64_e32 v[128:129], v[240:241]
	v_mov_b64_e32 v[130:131], v[242:243]
	s_nop 0
	v_mov_b64_e32 v[160:161], v[244:245]
	v_mov_b64_e32 v[162:163], v[246:247]
	global_load_dwordx4 v[240:243], v[248:249], off offset:3072 nt
	global_load_dwordx4 v[244:247], v[250:251], off offset:3072
	v_lshlrev_b32_e32 v172, 16, v128
	v_lshlrev_b32_e32 v136, 16, v160
	v_and_b32_e32 v173, 0xffff0000, v128
	v_lshlrev_b32_e32 v128, 16, v161
	v_rcp_f32_e32 v170, v136
	v_and_b32_e32 v136, 0xffff0000, v160
	v_rcp_f32_e32 v160, v128
	v_and_b32_e32 v128, 0xffff0000, v161
	v_rcp_f32_e32 v161, v128
	v_lshlrev_b32_e32 v128, 16, v129
	v_and_b32_e32 v129, 0xffff0000, v129
	v_rcp_f32_e32 v171, v136
	v_pk_mul_f32 v[128:129], v[160:161], v[128:129]
	v_lshlrev_b32_e32 v160, 16, v130
	v_pk_mul_f32 v[110:111], v[110:111], v[128:129]
	v_lshlrev_b32_e32 v128, 16, v162
	v_and_b32_e32 v129, 0xffff0000, v162
	v_rcp_f32_e32 v128, v128
	v_rcp_f32_e32 v129, v129
	v_and_b32_e32 v161, 0xffff0000, v130
	v_lshlrev_b32_e32 v130, 16, v131
	v_and_b32_e32 v131, 0xffff0000, v131
	v_pk_mul_f32 v[128:129], v[128:129], v[160:161]
	v_add_co_u32_e32 v160, vcc, s51, v158
	v_pk_mul_f32 v[112:113], v[112:113], v[128:129]
	v_lshlrev_b32_e32 v128, 16, v163
	v_and_b32_e32 v129, 0xffff0000, v163
	v_rcp_f32_e32 v128, v128
	v_rcp_f32_e32 v129, v129
	v_pk_mul_f32 v[170:171], v[170:171], v[172:173]
	v_addc_co_u32_e32 v161, vcc, 0, v159, vcc
	v_pk_mul_f32 v[128:129], v[128:129], v[130:131]
	v_pk_mul_f32 v[108:109], v[108:109], v[170:171]
	v_pk_mul_f32 v[114:115], v[114:115], v[128:129]
	v_add_co_u32_e32 v162, vcc, s51, v156
	s_waitcnt vmcnt(14)
	v_mov_b64_e32 v[128:129], v[184:185]
	v_mov_b64_e32 v[130:131], v[186:187]
	s_nop 0
	v_addc_co_u32_e32 v163, vcc, 0, v157, vcc
	v_mov_b64_e32 v[170:171], v[188:189]
	v_mov_b64_e32 v[172:173], v[190:191]
	v_add_co_u32_e32 v158, vcc, s83, v158
	v_lshlrev_b32_e32 v176, 16, v128
	v_and_b32_e32 v177, 0xffff0000, v128
	v_addc_co_u32_e32 v159, vcc, 0, v159, vcc
	v_lshlrev_b32_e32 v136, 16, v170
	v_lshlrev_b32_e32 v128, 16, v171
	v_rcp_f32_e32 v174, v136
	v_and_b32_e32 v136, 0xffff0000, v170
	v_rcp_f32_e32 v170, v128
	v_and_b32_e32 v128, 0xffff0000, v171
	v_rcp_f32_e32 v171, v128
	v_lshlrev_b32_e32 v128, 16, v129
	v_and_b32_e32 v129, 0xffff0000, v129
	v_rcp_f32_e32 v175, v136
	v_pk_mul_f32 v[128:129], v[170:171], v[128:129]
	v_lshlrev_b32_e32 v170, 16, v130
	v_pk_mul_f32 v[126:127], v[126:127], v[128:129]
	v_lshlrev_b32_e32 v128, 16, v172
	v_and_b32_e32 v129, 0xffff0000, v172
	v_rcp_f32_e32 v128, v128
	v_rcp_f32_e32 v129, v129
	v_and_b32_e32 v171, 0xffff0000, v130
	v_lshlrev_b32_e32 v130, 16, v131
	v_and_b32_e32 v131, 0xffff0000, v131
	v_pk_mul_f32 v[128:129], v[128:129], v[170:171]
	v_pk_mul_f32 v[174:175], v[174:175], v[176:177]
	v_pk_mul_f32 v[120:121], v[120:121], v[128:129]
	v_lshlrev_b32_e32 v128, 16, v173
	v_and_b32_e32 v129, 0xffff0000, v173
	v_rcp_f32_e32 v128, v128
	v_rcp_f32_e32 v129, v129
	v_pk_mul_f32 v[124:125], v[124:125], v[174:175]
	v_add_co_u32_e32 v156, vcc, s83, v156
	v_pk_mul_f32 v[128:129], v[128:129], v[130:131]
	s_nop 0
	v_addc_co_u32_e32 v157, vcc, 0, v157, vcc
	v_pk_mul_f32 v[122:123], v[122:123], v[128:129]
	s_waitcnt vmcnt(12)
	v_mov_b64_e32 v[128:129], v[192:193]
	v_mov_b64_e32 v[130:131], v[194:195]
	v_mov_b64_e32 v[170:171], v[196:197]
	v_mov_b64_e32 v[172:173], v[198:199]
	s_and_b64 vcc, exec, s[0:1]
	v_lshlrev_b32_e32 v176, 16, v128
	v_lshlrev_b32_e32 v136, 16, v170
	v_and_b32_e32 v177, 0xffff0000, v128
	v_lshlrev_b32_e32 v128, 16, v171
	v_rcp_f32_e32 v174, v136
	v_and_b32_e32 v136, 0xffff0000, v170
	v_rcp_f32_e32 v170, v128
	v_and_b32_e32 v128, 0xffff0000, v171
	v_rcp_f32_e32 v171, v128
	v_lshlrev_b32_e32 v128, 16, v129
	v_and_b32_e32 v129, 0xffff0000, v129
	v_rcp_f32_e32 v175, v136
	v_pk_mul_f32 v[128:129], v[170:171], v[128:129]
	v_lshlrev_b32_e32 v170, 16, v130
	v_pk_mul_f32 v[118:119], v[118:119], v[128:129]
	v_lshlrev_b32_e32 v128, 16, v172
	v_and_b32_e32 v129, 0xffff0000, v172
	v_rcp_f32_e32 v128, v128
	v_rcp_f32_e32 v129, v129
	v_and_b32_e32 v171, 0xffff0000, v130
	v_lshlrev_b32_e32 v130, 16, v131
	v_and_b32_e32 v131, 0xffff0000, v131
	v_pk_mul_f32 v[128:129], v[128:129], v[170:171]
	v_pk_mul_f32 v[174:175], v[174:175], v[176:177]
	v_pk_mul_f32 v[96:97], v[96:97], v[128:129]
	v_lshlrev_b32_e32 v128, 16, v173
	v_and_b32_e32 v129, 0xffff0000, v173
	v_rcp_f32_e32 v128, v128
	v_rcp_f32_e32 v129, v129
	v_pk_mul_f32 v[116:117], v[116:117], v[174:175]
	v_pk_mul_f32 v[128:129], v[128:129], v[130:131]
	s_nop 0
	v_pk_mul_f32 v[98:99], v[98:99], v[128:129]
	s_nop 0
	s_waitcnt vmcnt(10)
	v_mov_b64_e32 v[128:129], v[200:201]
	v_mov_b64_e32 v[130:131], v[202:203]
	v_mov_b64_e32 v[170:171], v[204:205]
	v_mov_b64_e32 v[172:173], v[206:207]
	v_lshlrev_b32_e32 v176, 16, v128
	v_lshlrev_b32_e32 v136, 16, v170
	v_and_b32_e32 v177, 0xffff0000, v128
	v_lshlrev_b32_e32 v128, 16, v171
	v_rcp_f32_e32 v174, v136
	v_and_b32_e32 v136, 0xffff0000, v170
	v_rcp_f32_e32 v170, v128
	v_and_b32_e32 v128, 0xffff0000, v171
	v_rcp_f32_e32 v171, v128
	v_lshlrev_b32_e32 v128, 16, v129
	v_and_b32_e32 v129, 0xffff0000, v129
	v_rcp_f32_e32 v175, v136
	v_pk_mul_f32 v[128:129], v[170:171], v[128:129]
	v_lshlrev_b32_e32 v170, 16, v130
	v_pk_mul_f32 v[94:95], v[94:95], v[128:129]
	v_lshlrev_b32_e32 v128, 16, v172
	v_and_b32_e32 v129, 0xffff0000, v172
	v_rcp_f32_e32 v128, v128
	v_rcp_f32_e32 v129, v129
	v_and_b32_e32 v171, 0xffff0000, v130
	v_lshlrev_b32_e32 v130, 16, v131
	v_and_b32_e32 v131, 0xffff0000, v131
	v_pk_mul_f32 v[128:129], v[128:129], v[170:171]
	v_pk_mul_f32 v[174:175], v[174:175], v[176:177]
	v_pk_mul_f32 v[88:89], v[88:89], v[128:129]
	v_lshlrev_b32_e32 v128, 16, v173
	v_and_b32_e32 v129, 0xffff0000, v173
	v_rcp_f32_e32 v128, v128
	v_rcp_f32_e32 v129, v129
	v_pk_mul_f32 v[92:93], v[92:93], v[174:175]
	v_pk_mul_f32 v[128:129], v[128:129], v[130:131]
	s_nop 0
	v_pk_mul_f32 v[90:91], v[90:91], v[128:129]
	s_waitcnt vmcnt(8)
	v_mov_b64_e32 v[128:129], v[208:209]
	v_mov_b64_e32 v[130:131], v[210:211]
	s_nop 0
	v_mov_b64_e32 v[160:161], v[212:213]
	v_mov_b64_e32 v[162:163], v[214:215]
	v_lshlrev_b32_e32 v172, 16, v128
	v_lshlrev_b32_e32 v136, 16, v160
	v_and_b32_e32 v173, 0xffff0000, v128
	v_lshlrev_b32_e32 v128, 16, v161
	v_rcp_f32_e32 v170, v136
	v_and_b32_e32 v136, 0xffff0000, v160
	v_rcp_f32_e32 v160, v128
	v_and_b32_e32 v128, 0xffff0000, v161
	v_rcp_f32_e32 v161, v128
	v_lshlrev_b32_e32 v128, 16, v129
	v_and_b32_e32 v129, 0xffff0000, v129
	v_rcp_f32_e32 v171, v136
	v_pk_mul_f32 v[128:129], v[160:161], v[128:129]
	v_lshlrev_b32_e32 v160, 16, v130
	v_pk_mul_f32 v[78:79], v[78:79], v[128:129]
	v_lshlrev_b32_e32 v128, 16, v162
	v_and_b32_e32 v129, 0xffff0000, v162
	v_rcp_f32_e32 v128, v128
	v_rcp_f32_e32 v129, v129
	v_and_b32_e32 v161, 0xffff0000, v130
	v_lshlrev_b32_e32 v130, 16, v131
	v_and_b32_e32 v131, 0xffff0000, v131
	v_pk_mul_f32 v[128:129], v[128:129], v[160:161]
	v_pk_mul_f32 v[170:171], v[170:171], v[172:173]
	v_pk_mul_f32 v[72:73], v[72:73], v[128:129]
	v_lshlrev_b32_e32 v128, 16, v163
	v_and_b32_e32 v129, 0xffff0000, v163
	v_rcp_f32_e32 v128, v128
	v_rcp_f32_e32 v129, v129
	v_pk_mul_f32 v[76:77], v[76:77], v[170:171]
	v_pk_mul_f32 v[128:129], v[128:129], v[130:131]
	s_nop 0
	v_pk_mul_f32 v[74:75], v[74:75], v[128:129]
	s_nop 0
	s_waitcnt vmcnt(6)
	v_mov_b64_e32 v[128:129], v[216:217]
	v_mov_b64_e32 v[130:131], v[218:219]
	v_mov_b64_e32 v[160:161], v[220:221]
	v_mov_b64_e32 v[162:163], v[222:223]
	v_lshlrev_b32_e32 v172, 16, v128
	v_lshlrev_b32_e32 v136, 16, v160
	v_and_b32_e32 v173, 0xffff0000, v128
	v_lshlrev_b32_e32 v128, 16, v161
	v_rcp_f32_e32 v170, v136
	v_and_b32_e32 v136, 0xffff0000, v160
	v_rcp_f32_e32 v160, v128
	v_and_b32_e32 v128, 0xffff0000, v161
	v_rcp_f32_e32 v161, v128
	v_lshlrev_b32_e32 v128, 16, v129
	v_and_b32_e32 v129, 0xffff0000, v129
	v_rcp_f32_e32 v171, v136
	v_pk_mul_f32 v[128:129], v[160:161], v[128:129]
	v_lshlrev_b32_e32 v160, 16, v130
	v_pk_mul_f32 v[62:63], v[62:63], v[128:129]
	v_lshlrev_b32_e32 v128, 16, v162
	v_and_b32_e32 v129, 0xffff0000, v162
	v_rcp_f32_e32 v128, v128
	v_rcp_f32_e32 v129, v129
	v_and_b32_e32 v161, 0xffff0000, v130
	v_lshlrev_b32_e32 v130, 16, v131
	v_and_b32_e32 v131, 0xffff0000, v131
	v_pk_mul_f32 v[128:129], v[128:129], v[160:161]
	v_pk_mul_f32 v[170:171], v[170:171], v[172:173]
	v_pk_mul_f32 v[56:57], v[56:57], v[128:129]
	v_lshlrev_b32_e32 v128, 16, v163
	v_and_b32_e32 v129, 0xffff0000, v163
	v_rcp_f32_e32 v128, v128
	v_rcp_f32_e32 v129, v129
	v_pk_mul_f32 v[60:61], v[60:61], v[170:171]
	v_pk_mul_f32 v[128:129], v[128:129], v[130:131]
	s_nop 0
	v_pk_mul_f32 v[58:59], v[58:59], v[128:129]
	s_waitcnt vmcnt(4)
	v_mov_b64_e32 v[128:129], v[224:225]
	v_mov_b64_e32 v[130:131], v[226:227]
	v_mov_b64_e32 v[160:161], v[228:229]
	v_mov_b64_e32 v[162:163], v[230:231]
	v_lshlrev_b32_e32 v172, 16, v128
	v_lshlrev_b32_e32 v136, 16, v160
	v_and_b32_e32 v173, 0xffff0000, v128
	v_lshlrev_b32_e32 v128, 16, v161
	v_rcp_f32_e32 v170, v136
	v_and_b32_e32 v136, 0xffff0000, v160
	v_rcp_f32_e32 v160, v128
	v_and_b32_e32 v128, 0xffff0000, v161
	v_rcp_f32_e32 v161, v128
	v_lshlrev_b32_e32 v128, 16, v129
	v_and_b32_e32 v129, 0xffff0000, v129
	v_rcp_f32_e32 v171, v136
	v_pk_mul_f32 v[128:129], v[160:161], v[128:129]
	v_lshlrev_b32_e32 v160, 16, v130
	v_pk_mul_f32 v[38:39], v[38:39], v[128:129]
	v_lshlrev_b32_e32 v128, 16, v162
	v_and_b32_e32 v129, 0xffff0000, v162
	v_rcp_f32_e32 v128, v128
	v_rcp_f32_e32 v129, v129
	v_and_b32_e32 v161, 0xffff0000, v130
	v_lshlrev_b32_e32 v130, 16, v131
	v_and_b32_e32 v131, 0xffff0000, v131
	v_pk_mul_f32 v[128:129], v[128:129], v[160:161]
	v_pk_mul_f32 v[170:171], v[170:171], v[172:173]
	v_pk_mul_f32 v[24:25], v[24:25], v[128:129]
	v_lshlrev_b32_e32 v128, 16, v163
	v_and_b32_e32 v129, 0xffff0000, v163
	v_rcp_f32_e32 v128, v128
	v_rcp_f32_e32 v129, v129
	v_pk_mul_f32 v[36:37], v[36:37], v[170:171]
	v_pk_mul_f32 v[128:129], v[128:129], v[130:131]
	s_nop 0
	v_pk_mul_f32 v[26:27], v[26:27], v[128:129]
	s_nop 0
	s_waitcnt vmcnt(2)
	v_mov_b64_e32 v[128:129], v[232:233]
	v_mov_b64_e32 v[130:131], v[234:235]
	v_mov_b64_e32 v[160:161], v[236:237]
	v_mov_b64_e32 v[162:163], v[238:239]
	v_lshlrev_b32_e32 v172, 16, v128
	v_lshlrev_b32_e32 v136, 16, v160
	v_and_b32_e32 v173, 0xffff0000, v128
	v_lshlrev_b32_e32 v128, 16, v161
	v_rcp_f32_e32 v170, v136
	v_and_b32_e32 v136, 0xffff0000, v160
	v_rcp_f32_e32 v160, v128
	v_and_b32_e32 v128, 0xffff0000, v161
	v_rcp_f32_e32 v161, v128
	v_lshlrev_b32_e32 v128, 16, v129
	v_and_b32_e32 v129, 0xffff0000, v129
	v_rcp_f32_e32 v171, v136
	v_pk_mul_f32 v[128:129], v[160:161], v[128:129]
	v_lshlrev_b32_e32 v160, 16, v130
	v_pk_mul_f32 v[22:23], v[22:23], v[128:129]
	v_lshlrev_b32_e32 v128, 16, v162
	v_and_b32_e32 v129, 0xffff0000, v162
	v_rcp_f32_e32 v128, v128
	v_rcp_f32_e32 v129, v129
	v_and_b32_e32 v161, 0xffff0000, v130
	v_lshlrev_b32_e32 v130, 16, v131
	v_and_b32_e32 v131, 0xffff0000, v131
	v_pk_mul_f32 v[128:129], v[128:129], v[160:161]
	v_pk_mul_f32 v[170:171], v[170:171], v[172:173]
	v_pk_mul_f32 v[16:17], v[16:17], v[128:129]
	v_lshlrev_b32_e32 v128, 16, v163
	v_and_b32_e32 v129, 0xffff0000, v163
	v_rcp_f32_e32 v128, v128
	v_rcp_f32_e32 v129, v129
	v_pk_mul_f32 v[20:21], v[20:21], v[170:171]
	v_pk_mul_f32 v[128:129], v[128:129], v[130:131]
	s_nop 0
	v_pk_mul_f32 v[18:19], v[18:19], v[128:129]
	s_waitcnt vmcnt(0)
	v_mov_b64_e32 v[128:129], v[240:241]
	v_mov_b64_e32 v[130:131], v[242:243]
	s_nop 0
	v_mov_b64_e32 v[156:157], v[244:245]
	v_mov_b64_e32 v[158:159], v[246:247]
	v_lshlrev_b32_e32 v162, 16, v128
	v_lshlrev_b32_e32 v136, 16, v156
	v_and_b32_e32 v163, 0xffff0000, v128
	v_lshlrev_b32_e32 v128, 16, v157
	v_rcp_f32_e32 v160, v136
	v_and_b32_e32 v136, 0xffff0000, v156
	v_rcp_f32_e32 v156, v128
	v_and_b32_e32 v128, 0xffff0000, v157
	v_rcp_f32_e32 v157, v128
	v_lshlrev_b32_e32 v128, 16, v129
	v_and_b32_e32 v129, 0xffff0000, v129
	v_rcp_f32_e32 v161, v136
	v_pk_mul_f32 v[128:129], v[156:157], v[128:129]
	v_lshlrev_b32_e32 v156, 16, v130
	v_pk_mul_f32 v[6:7], v[6:7], v[128:129]
	v_lshlrev_b32_e32 v128, 16, v158
	v_and_b32_e32 v129, 0xffff0000, v158
	v_rcp_f32_e32 v128, v128
	v_rcp_f32_e32 v129, v129
	v_and_b32_e32 v157, 0xffff0000, v130
	v_lshlrev_b32_e32 v130, 16, v131
	v_and_b32_e32 v131, 0xffff0000, v131
	v_pk_mul_f32 v[128:129], v[128:129], v[156:157]
	v_pk_mul_f32 v[160:161], v[160:161], v[162:163]
	v_pk_mul_f32 v[0:1], v[0:1], v[128:129]
	v_lshlrev_b32_e32 v128, 16, v159
	v_and_b32_e32 v129, 0xffff0000, v159
	v_rcp_f32_e32 v128, v128
	v_rcp_f32_e32 v129, v129
	v_pk_mul_f32 v[4:5], v[4:5], v[160:161]
	v_pk_mul_f32 v[128:129], v[128:129], v[130:131]
	s_nop 0
	v_pk_mul_f32 v[2:3], v[2:3], v[128:129]
	s_nop 0
	s_cbranch_vccnz .LBB0_772
	s_barrier
	s_branch .Lpadskip_2
	s_nop 0
	s_nop 0
	s_nop 0
	s_nop 0
	s_nop 0
	s_nop 0
	s_nop 0
	s_nop 0
	s_nop 0
	s_nop 0
	s_nop 0
	s_nop 0
	s_nop 0
	s_nop 0
	s_nop 0
	s_nop 0
	s_nop 0
	s_nop 0
	s_nop 0
	s_nop 0
	s_nop 0
	s_nop 0
	s_nop 0
	s_nop 0
	s_nop 0
	s_nop 0
	s_nop 0
	s_nop 0
	s_nop 0
	s_nop 0
	s_nop 0
	s_nop 0
	s_nop 0
	s_nop 0
	s_nop 0
	s_nop 0
	s_nop 0
	s_nop 0
	s_nop 0
	s_nop 0
	s_nop 0
	s_nop 0
	s_nop 0
	s_nop 0
	s_nop 0
	s_nop 0
	s_nop 0
.Lpadskip_2:
.LBB0_772:
	s_add_i32 s85, s85, 1
	v_readlane_b32 s2, v252, 26
	s_mul_hi_u32 s3, s85, s2
	s_mul_i32 s2, s85, s2
	v_readlane_b32 s4, v252, 0
	s_add_u32 s2, s2, s4
	s_addc_u32 s3, s3, 0
	v_cmp_lt_u64_e64 s[4:5], s[2:3], v[154:155]
	s_lshl_b32 s3, s2, 3
	s_and_b32 s3, s3, 56
	s_bfe_u32 s34, s2, 0x30003
	s_or_b32 s3, s34, s3
	s_lshr_b32 s2, s2, 6
	s_and_b64 s[34:35], s[4:5], exec
	s_cselect_b32 s34, s3, s87
	s_cselect_b32 s36, s2, s86
	s_ashr_i32 s35, s34, 31
	s_lshl_b64 s[38:39], s[34:35], 20
	v_readlane_b32 s34, v252, 6
	v_readlane_b32 s35, v252, 7
	s_add_u32 s37, s34, s38
	s_addc_u32 s48, s35, s39
	s_and_b64 s[34:35], s[4:5], exec
	s_cselect_b32 s33, s48, s33
	s_cselect_b32 s43, s37, s43
	s_ashr_i32 s37, s36, 31
	s_lshl_b64 s[36:37], s[36:37], 20
	s_add_u32 s48, s40, s36
	s_addc_u32 s49, s41, s37
	s_and_b64 s[34:35], s[4:5], exec
	s_cselect_b32 s42, s49, s42
	s_cselect_b32 s11, s48, s11
	s_add_u32 s48, s78, s28
	v_lshl_add_u64 v[128:129], v[150:151], 0, s[26:27]
	v_lshl_add_u64 v[130:131], v[152:153], 0, s[26:27]
	s_addc_u32 s49, s79, s29
	s_mov_b32 s86, -2
	s_mov_b64 s[26:27], 0

.LBB0_776:
	v_mov_b32_e32 v128, v182
	s_mov_b64 s[10:11], s[16:17]
	v_and_b32_e32 v128, 63, v128
	v_readlane_b32 s96, v252, 26
	v_ashrrev_i32_e32 v129, 31, v128
	v_lshl_add_u64 v[130:131], v[128:129], 4, s[10:11]
	v_lshl_add_u64 v[130:131], v[130:131], 0, s[30:31]
	s_mov_b64 s[98:99], 0x1000
	v_mov_b64_e32 v[248:249], v[130:131]
	global_load_dwordx4 v[184:187], v[248:249], off nt
	global_load_dwordx4 v[188:191], v[248:249], off offset:1024 nt
	global_load_dwordx4 v[192:195], v[248:249], off offset:2048 nt
	global_load_dwordx4 v[196:199], v[248:249], off offset:3072 nt
	v_lshl_add_u64 v[248:249], v[248:249], 0, s[98:99]
	global_load_dwordx4 v[200:203], v[248:249], off nt
	global_load_dwordx4 v[204:207], v[248:249], off offset:1024 nt
	global_load_dwordx4 v[208:211], v[248:249], off offset:2048 nt
	global_load_dwordx4 v[212:215], v[248:249], off offset:3072 nt
	v_lshl_add_u64 v[248:249], v[248:249], 0, s[98:99]
	global_load_dwordx4 v[216:219], v[248:249], off nt
	global_load_dwordx4 v[220:223], v[248:249], off offset:1024 nt
	global_load_dwordx4 v[224:227], v[248:249], off offset:2048 nt
	global_load_dwordx4 v[228:231], v[248:249], off offset:3072 nt
	v_lshl_add_u64 v[248:249], v[248:249], 0, s[98:99]
	global_load_dwordx4 v[232:235], v[248:249], off nt
	global_load_dwordx4 v[236:239], v[248:249], off offset:1024 nt
	global_load_dwordx4 v[240:243], v[248:249], off offset:2048 nt
	global_load_dwordx4 v[244:247], v[248:249], off offset:3072 nt
	s_waitcnt vmcnt(15)
	s_nop 1
	v_mov_b64_e32 v[160:161], v[184:185]
	v_mov_b64_e32 v[162:163], v[186:187]
	s_lshl_b32 s10, s12, 8
	s_add_i32 s10, s10, s52
	v_and_or_b32 v158, v128, 15, s10
	v_ashrrev_i32_e32 v128, 1, v128
	v_and_b32_e32 v128, -8, v128
	v_ashrrev_i32_e32 v159, 31, v158
	s_lshl_b32 s12, s24, 8
	v_add_u32_e32 v128, s53, v128
	v_lshlrev_b64 v[156:157], 12, v[158:159]
	s_lshl_b64 s[24:25], s[12:13], 1
	v_lshl_add_u64 v[156:157], s[8:9], 0, v[156:157]
	v_ashrrev_i32_e32 v129, 31, v128
	v_lshl_add_u64 v[168:169], v[156:157], 0, s[24:25]
	v_lshlrev_b64 v[156:157], 1, v[128:129]
	v_lshl_add_u64 v[128:129], v[168:169], 0, v[156:157]
	s_mov_b32 s10, 0x80000
	v_lshlrev_b32_e32 v168, 16, v160
	v_and_b32_e32 v169, 0xffff0000, v160
	v_lshlrev_b32_e32 v160, 16, v161
	v_and_b32_e32 v161, 0xffff0000, v161
	v_lshlrev_b32_e32 v170, 16, v162
	v_and_b32_e32 v171, 0xffff0000, v162
	v_lshlrev_b32_e32 v162, 16, v163
	v_and_b32_e32 v163, 0xffff0000, v163
	v_pk_mul_f32 v[8:9], v[8:9], v[168:169]
	v_pk_mul_f32 v[10:11], v[10:11], v[160:161]
	v_pk_mul_f32 v[12:13], v[12:13], v[170:171]
	v_pk_mul_f32 v[14:15], v[14:15], v[162:163]
	v_cvt_pk_bf16_f32 v8, v8, v9
	v_cvt_pk_bf16_f32 v9, v10, v11
	v_cvt_pk_bf16_f32 v10, v12, v13
	v_cvt_pk_bf16_f32 v11, v14, v15
	global_store_dwordx4 v[128:129], v[8:11], off
	s_waitcnt vmcnt(15)
	s_nop 1
	v_mov_b64_e32 v[8:9], v[188:189]
	v_mov_b64_e32 v[10:11], v[190:191]
	v_lshlrev_b32_e32 v12, 16, v8
	v_and_b32_e32 v13, 0xffff0000, v8
	v_lshlrev_b32_e32 v8, 16, v9
	v_and_b32_e32 v9, 0xffff0000, v9
	v_lshlrev_b32_e32 v14, 16, v10
	v_and_b32_e32 v15, 0xffff0000, v10
	v_lshlrev_b32_e32 v10, 16, v11
	v_and_b32_e32 v11, 0xffff0000, v11
	v_pk_mul_f32 v[12:13], v[28:29], v[12:13]
	v_pk_mul_f32 v[28:29], v[30:31], v[8:9]
	v_pk_mul_f32 v[14:15], v[32:33], v[14:15]
	v_pk_mul_f32 v[30:31], v[34:35], v[10:11]
	v_cvt_pk_bf16_f32 v8, v12, v13
	v_cvt_pk_bf16_f32 v9, v28, v29
	v_cvt_pk_bf16_f32 v10, v14, v15
	v_cvt_pk_bf16_f32 v11, v30, v31
	global_store_dwordx4 v[128:129], v[8:11], off offset:256
	s_waitcnt vmcnt(15)
	s_nop 1
	v_mov_b64_e32 v[8:9], v[192:193]
	v_mov_b64_e32 v[10:11], v[194:195]
	v_or_b32_e32 v12, 16, v158
	v_ashrrev_i32_e32 v13, 31, v12
	v_lshlrev_b64 v[12:13], 12, v[12:13]
	v_lshl_add_u64 v[12:13], s[8:9], 0, v[12:13]
	v_lshl_add_u64 v[12:13], v[12:13], 0, s[24:25]
	v_lshl_add_u64 v[12:13], v[12:13], 0, v[156:157]
	v_lshlrev_b32_e32 v14, 16, v8
	v_and_b32_e32 v15, 0xffff0000, v8
	v_lshlrev_b32_e32 v8, 16, v9
	v_and_b32_e32 v9, 0xffff0000, v9
	v_lshlrev_b32_e32 v28, 16, v10
	v_and_b32_e32 v29, 0xffff0000, v10
	v_lshlrev_b32_e32 v10, 16, v11
	v_and_b32_e32 v11, 0xffff0000, v11
	v_pk_mul_f32 v[14:15], v[40:41], v[14:15]
	v_pk_mul_f32 v[30:31], v[42:43], v[8:9]
	v_pk_mul_f32 v[28:29], v[44:45], v[28:29]
	v_pk_mul_f32 v[32:33], v[46:47], v[10:11]
	v_cvt_pk_bf16_f32 v8, v14, v15
	v_cvt_pk_bf16_f32 v9, v30, v31
	v_cvt_pk_bf16_f32 v10, v28, v29
	v_cvt_pk_bf16_f32 v11, v32, v33
	global_store_dwordx4 v[12:13], v[8:11], off
	s_waitcnt vmcnt(15)
	s_nop 1
	v_mov_b64_e32 v[8:9], v[196:197]
	v_mov_b64_e32 v[10:11], v[198:199]
	v_add_co_u32_e32 v14, vcc, s82, v130
	v_lshlrev_b32_e32 v28, 16, v8
	v_and_b32_e32 v29, 0xffff0000, v8
	v_lshlrev_b32_e32 v8, 16, v9
	v_and_b32_e32 v9, 0xffff0000, v9
	v_lshlrev_b32_e32 v30, 16, v10
	v_and_b32_e32 v31, 0xffff0000, v10
	v_lshlrev_b32_e32 v10, 16, v11
	v_and_b32_e32 v11, 0xffff0000, v11
	v_pk_mul_f32 v[28:29], v[48:49], v[28:29]
	v_pk_mul_f32 v[32:33], v[50:51], v[8:9]
	v_pk_mul_f32 v[30:31], v[52:53], v[30:31]
	v_pk_mul_f32 v[34:35], v[54:55], v[10:11]
	v_cvt_pk_bf16_f32 v8, v28, v29
	v_cvt_pk_bf16_f32 v9, v32, v33
	v_cvt_pk_bf16_f32 v10, v30, v31
	v_cvt_pk_bf16_f32 v11, v34, v35
	global_store_dwordx4 v[12:13], v[8:11], off offset:256
	v_addc_co_u32_e32 v15, vcc, 0, v131, vcc
	s_waitcnt vmcnt(15)
	s_nop 1
	v_mov_b64_e32 v[8:9], v[200:201]
	v_mov_b64_e32 v[10:11], v[202:203]
	v_or_b32_e32 v12, 32, v158
	v_ashrrev_i32_e32 v13, 31, v12
	v_lshlrev_b64 v[12:13], 12, v[12:13]
	v_lshl_add_u64 v[12:13], s[8:9], 0, v[12:13]
	v_lshl_add_u64 v[12:13], v[12:13], 0, s[24:25]
	v_lshl_add_u64 v[12:13], v[12:13], 0, v[156:157]
	v_lshlrev_b32_e32 v28, 16, v8
	v_and_b32_e32 v29, 0xffff0000, v8
	v_lshlrev_b32_e32 v8, 16, v9
	v_and_b32_e32 v9, 0xffff0000, v9
	v_lshlrev_b32_e32 v30, 16, v10
	v_and_b32_e32 v31, 0xffff0000, v10
	v_lshlrev_b32_e32 v10, 16, v11
	v_and_b32_e32 v11, 0xffff0000, v11
	v_pk_mul_f32 v[28:29], v[64:65], v[28:29]
	v_pk_mul_f32 v[32:33], v[66:67], v[8:9]
	v_pk_mul_f32 v[30:31], v[68:69], v[30:31]
	v_pk_mul_f32 v[34:35], v[70:71], v[10:11]
	v_cvt_pk_bf16_f32 v8, v28, v29
	v_cvt_pk_bf16_f32 v9, v32, v33
	v_cvt_pk_bf16_f32 v10, v30, v31
	v_cvt_pk_bf16_f32 v11, v34, v35
	global_store_dwordx4 v[12:13], v[8:11], off
	s_waitcnt vmcnt(15)
	s_nop 1
	v_mov_b64_e32 v[8:9], v[204:205]
	v_mov_b64_e32 v[10:11], v[206:207]
	v_lshlrev_b32_e32 v28, 16, v8
	v_and_b32_e32 v29, 0xffff0000, v8
	v_lshlrev_b32_e32 v8, 16, v9
	v_and_b32_e32 v9, 0xffff0000, v9
	v_lshlrev_b32_e32 v30, 16, v10
	v_and_b32_e32 v31, 0xffff0000, v10
	v_lshlrev_b32_e32 v10, 16, v11
	v_and_b32_e32 v11, 0xffff0000, v11
	v_pk_mul_f32 v[28:29], v[80:81], v[28:29]
	v_pk_mul_f32 v[32:33], v[82:83], v[8:9]
	v_pk_mul_f32 v[30:31], v[84:85], v[30:31]
	v_pk_mul_f32 v[34:35], v[86:87], v[10:11]
	v_cvt_pk_bf16_f32 v8, v28, v29
	v_cvt_pk_bf16_f32 v9, v32, v33
	v_cvt_pk_bf16_f32 v10, v30, v31
	v_cvt_pk_bf16_f32 v11, v34, v35
	global_store_dwordx4 v[12:13], v[8:11], off offset:256
	s_waitcnt vmcnt(15)
	s_nop 1
	v_mov_b64_e32 v[8:9], v[208:209]
	v_mov_b64_e32 v[10:11], v[210:211]
	v_or_b32_e32 v12, 48, v158
	v_ashrrev_i32_e32 v13, 31, v12
	v_lshlrev_b64 v[12:13], 12, v[12:13]
	v_lshl_add_u64 v[12:13], s[8:9], 0, v[12:13]
	v_lshl_add_u64 v[12:13], v[12:13], 0, s[24:25]
	v_lshl_add_u64 v[12:13], v[12:13], 0, v[156:157]
	v_lshlrev_b32_e32 v28, 16, v8
	v_and_b32_e32 v29, 0xffff0000, v8
	v_lshlrev_b32_e32 v8, 16, v9
	v_and_b32_e32 v9, 0xffff0000, v9
	v_lshlrev_b32_e32 v30, 16, v10
	v_and_b32_e32 v31, 0xffff0000, v10
	v_lshlrev_b32_e32 v10, 16, v11
	v_and_b32_e32 v11, 0xffff0000, v11
	v_pk_mul_f32 v[28:29], v[100:101], v[28:29]
	v_pk_mul_f32 v[32:33], v[102:103], v[8:9]
	v_pk_mul_f32 v[30:31], v[104:105], v[30:31]
	v_pk_mul_f32 v[34:35], v[106:107], v[10:11]
	v_cvt_pk_bf16_f32 v8, v28, v29
	v_cvt_pk_bf16_f32 v9, v32, v33
	v_cvt_pk_bf16_f32 v10, v30, v31
	v_cvt_pk_bf16_f32 v11, v34, v35
	global_store_dwordx4 v[12:13], v[8:11], off
	s_waitcnt vmcnt(15)
	s_nop 1
	v_mov_b64_e32 v[8:9], v[212:213]
	v_mov_b64_e32 v[10:11], v[214:215]
	v_add_co_u32_e32 v14, vcc, s51, v130
	v_lshlrev_b32_e32 v28, 16, v8
	v_and_b32_e32 v29, 0xffff0000, v8
	v_lshlrev_b32_e32 v8, 16, v9
	v_and_b32_e32 v9, 0xffff0000, v9
	v_lshlrev_b32_e32 v30, 16, v10
	v_and_b32_e32 v31, 0xffff0000, v10
	v_lshlrev_b32_e32 v10, 16, v11
	v_and_b32_e32 v11, 0xffff0000, v11
	v_pk_mul_f32 v[28:29], v[108:109], v[28:29]
	v_pk_mul_f32 v[32:33], v[110:111], v[8:9]
	v_pk_mul_f32 v[30:31], v[112:113], v[30:31]
	v_pk_mul_f32 v[34:35], v[114:115], v[10:11]
	v_cvt_pk_bf16_f32 v8, v28, v29
	v_cvt_pk_bf16_f32 v9, v32, v33
	v_cvt_pk_bf16_f32 v10, v30, v31
	v_cvt_pk_bf16_f32 v11, v34, v35
	global_store_dwordx4 v[12:13], v[8:11], off offset:256
	v_addc_co_u32_e32 v15, vcc, 0, v131, vcc
	s_waitcnt vmcnt(15)
	s_nop 1
	v_mov_b64_e32 v[8:9], v[216:217]
	v_mov_b64_e32 v[10:11], v[218:219]
	v_add_co_u32_e32 v12, vcc, s10, v128
	s_mov_b64 s[10:11], 0x80000
	s_nop 0
	v_addc_co_u32_e32 v13, vcc, 0, v129, vcc
	v_lshlrev_b32_e32 v28, 16, v8
	v_and_b32_e32 v29, 0xffff0000, v8
	v_lshlrev_b32_e32 v8, 16, v9
	v_and_b32_e32 v9, 0xffff0000, v9
	v_lshlrev_b32_e32 v30, 16, v10
	v_and_b32_e32 v31, 0xffff0000, v10
	v_lshlrev_b32_e32 v10, 16, v11
	v_and_b32_e32 v11, 0xffff0000, v11
	v_pk_mul_f32 v[28:29], v[124:125], v[28:29]
	v_pk_mul_f32 v[32:33], v[126:127], v[8:9]
	v_pk_mul_f32 v[30:31], v[120:121], v[30:31]
	v_pk_mul_f32 v[34:35], v[122:123], v[10:11]
	v_cvt_pk_bf16_f32 v8, v28, v29
	v_cvt_pk_bf16_f32 v9, v32, v33
	v_cvt_pk_bf16_f32 v10, v30, v31
	v_cvt_pk_bf16_f32 v11, v34, v35
	global_store_dwordx4 v[12:13], v[8:11], off
	s_waitcnt vmcnt(15)
	s_nop 1
	v_mov_b64_e32 v[8:9], v[220:221]
	v_mov_b64_e32 v[10:11], v[222:223]
	v_lshl_add_u64 v[12:13], v[128:129], 0, s[10:11]
	s_mov_b32 s10, 0x90000
	v_lshlrev_b32_e32 v28, 16, v8
	v_and_b32_e32 v29, 0xffff0000, v8
	v_lshlrev_b32_e32 v8, 16, v9
	v_and_b32_e32 v9, 0xffff0000, v9
	v_lshlrev_b32_e32 v30, 16, v10
	v_and_b32_e32 v31, 0xffff0000, v10
	v_lshlrev_b32_e32 v10, 16, v11
	v_and_b32_e32 v11, 0xffff0000, v11
	v_pk_mul_f32 v[28:29], v[116:117], v[28:29]
	v_pk_mul_f32 v[32:33], v[118:119], v[8:9]
	v_pk_mul_f32 v[30:31], v[96:97], v[30:31]
	v_pk_mul_f32 v[34:35], v[98:99], v[10:11]
	v_cvt_pk_bf16_f32 v8, v28, v29
	v_cvt_pk_bf16_f32 v9, v32, v33
	v_cvt_pk_bf16_f32 v10, v30, v31
	v_cvt_pk_bf16_f32 v11, v34, v35
	global_store_dwordx4 v[12:13], v[8:11], off offset:256
	s_waitcnt vmcnt(15)
	s_nop 1
	v_mov_b64_e32 v[8:9], v[224:225]
	v_mov_b64_e32 v[10:11], v[226:227]
	v_add_co_u32_e32 v12, vcc, s10, v128
	s_mov_b64 s[10:11], 0x90000
	s_nop 0
	v_addc_co_u32_e32 v13, vcc, 0, v129, vcc
	v_lshlrev_b32_e32 v28, 16, v8
	v_and_b32_e32 v29, 0xffff0000, v8
	v_lshlrev_b32_e32 v8, 16, v9
	v_and_b32_e32 v9, 0xffff0000, v9
	v_lshlrev_b32_e32 v30, 16, v10
	v_and_b32_e32 v31, 0xffff0000, v10
	v_lshlrev_b32_e32 v10, 16, v11
	v_and_b32_e32 v11, 0xffff0000, v11
	v_pk_mul_f32 v[28:29], v[92:93], v[28:29]
	v_pk_mul_f32 v[32:33], v[94:95], v[8:9]
	v_pk_mul_f32 v[30:31], v[88:89], v[30:31]
	v_pk_mul_f32 v[34:35], v[90:91], v[10:11]
	v_cvt_pk_bf16_f32 v8, v28, v29
	v_cvt_pk_bf16_f32 v9, v32, v33
	v_cvt_pk_bf16_f32 v10, v30, v31
	v_cvt_pk_bf16_f32 v11, v34, v35
	global_store_dwordx4 v[12:13], v[8:11], off
	s_waitcnt vmcnt(15)
	s_nop 1
	v_mov_b64_e32 v[8:9], v[228:229]
	v_mov_b64_e32 v[10:11], v[230:231]
	v_lshl_add_u64 v[14:15], v[128:129], 0, s[10:11]
	v_add_co_u32_e32 v12, vcc, s83, v130
	s_mov_b32 s10, 0xa0000
	s_nop 0
	v_addc_co_u32_e32 v13, vcc, 0, v131, vcc
	v_lshlrev_b32_e32 v28, 16, v8
	v_and_b32_e32 v29, 0xffff0000, v8
	v_lshlrev_b32_e32 v8, 16, v9
	v_and_b32_e32 v9, 0xffff0000, v9
	v_lshlrev_b32_e32 v30, 16, v10
	v_and_b32_e32 v31, 0xffff0000, v10
	v_lshlrev_b32_e32 v10, 16, v11
	v_and_b32_e32 v11, 0xffff0000, v11
	v_pk_mul_f32 v[28:29], v[76:77], v[28:29]
	v_pk_mul_f32 v[32:33], v[78:79], v[8:9]
	v_pk_mul_f32 v[30:31], v[72:73], v[30:31]
	v_pk_mul_f32 v[34:35], v[74:75], v[10:11]
	v_cvt_pk_bf16_f32 v8, v28, v29
	v_cvt_pk_bf16_f32 v9, v32, v33
	v_cvt_pk_bf16_f32 v10, v30, v31
	v_cvt_pk_bf16_f32 v11, v34, v35
	global_store_dwordx4 v[14:15], v[8:11], off offset:256
	s_waitcnt vmcnt(15)
	s_nop 1
	v_mov_b64_e32 v[8:9], v[232:233]
	v_mov_b64_e32 v[10:11], v[234:235]
	v_add_co_u32_e32 v14, vcc, s10, v128
	s_mov_b64 s[10:11], 0xa0000
	s_nop 0
	v_addc_co_u32_e32 v15, vcc, 0, v129, vcc
	v_lshlrev_b32_e32 v28, 16, v8
	v_and_b32_e32 v29, 0xffff0000, v8
	v_lshlrev_b32_e32 v8, 16, v9
	v_and_b32_e32 v9, 0xffff0000, v9
	v_lshlrev_b32_e32 v30, 16, v10
	v_and_b32_e32 v31, 0xffff0000, v10
	v_lshlrev_b32_e32 v10, 16, v11
	v_and_b32_e32 v11, 0xffff0000, v11
	v_pk_mul_f32 v[28:29], v[60:61], v[28:29]
	v_pk_mul_f32 v[32:33], v[62:63], v[8:9]
	v_pk_mul_f32 v[30:31], v[56:57], v[30:31]
	v_pk_mul_f32 v[34:35], v[58:59], v[10:11]
	v_cvt_pk_bf16_f32 v8, v28, v29
	v_cvt_pk_bf16_f32 v9, v32, v33
	v_cvt_pk_bf16_f32 v10, v30, v31
	v_cvt_pk_bf16_f32 v11, v34, v35
	global_store_dwordx4 v[14:15], v[8:11], off
	s_waitcnt vmcnt(15)
	s_nop 1
	v_mov_b64_e32 v[8:9], v[236:237]
	v_mov_b64_e32 v[10:11], v[238:239]
	v_lshl_add_u64 v[14:15], v[128:129], 0, s[10:11]
	s_mov_b32 s10, 0xb0000
	v_lshlrev_b32_e32 v28, 16, v8
	v_and_b32_e32 v29, 0xffff0000, v8
	v_lshlrev_b32_e32 v8, 16, v9
	v_and_b32_e32 v9, 0xffff0000, v9
	v_lshlrev_b32_e32 v30, 16, v10
	v_and_b32_e32 v31, 0xffff0000, v10
	v_lshlrev_b32_e32 v10, 16, v11
	v_and_b32_e32 v11, 0xffff0000, v11
	v_pk_mul_f32 v[28:29], v[36:37], v[28:29]
	v_pk_mul_f32 v[32:33], v[38:39], v[8:9]
	v_pk_mul_f32 v[24:25], v[24:25], v[30:31]
	v_pk_mul_f32 v[26:27], v[26:27], v[10:11]
	v_cvt_pk_bf16_f32 v8, v28, v29
	v_cvt_pk_bf16_f32 v9, v32, v33
	v_cvt_pk_bf16_f32 v10, v24, v25
	v_cvt_pk_bf16_f32 v11, v26, v27
	global_store_dwordx4 v[14:15], v[8:11], off offset:256
	s_waitcnt vmcnt(15)
	s_nop 1
	v_mov_b64_e32 v[8:9], v[240:241]
	v_mov_b64_e32 v[10:11], v[242:243]
	v_add_co_u32_e32 v14, vcc, s10, v128
	s_mov_b64 s[10:11], 0xb0000
	s_nop 0
	v_addc_co_u32_e32 v15, vcc, 0, v129, vcc
	s_andn2_b64 vcc, exec, s[4:5]
	s_mov_b64 s[4:5], -1
	v_lshlrev_b32_e32 v24, 16, v8
	v_and_b32_e32 v25, 0xffff0000, v8
	v_lshlrev_b32_e32 v8, 16, v9
	v_and_b32_e32 v9, 0xffff0000, v9
	v_lshlrev_b32_e32 v26, 16, v10
	v_and_b32_e32 v27, 0xffff0000, v10
	v_lshlrev_b32_e32 v10, 16, v11
	v_and_b32_e32 v11, 0xffff0000, v11
	v_pk_mul_f32 v[20:21], v[20:21], v[24:25]
	v_pk_mul_f32 v[22:23], v[22:23], v[8:9]
	v_pk_mul_f32 v[16:17], v[16:17], v[26:27]
	v_pk_mul_f32 v[18:19], v[18:19], v[10:11]
	v_cvt_pk_bf16_f32 v8, v20, v21
	v_cvt_pk_bf16_f32 v9, v22, v23
	v_cvt_pk_bf16_f32 v10, v16, v17
	v_cvt_pk_bf16_f32 v11, v18, v19
	global_store_dwordx4 v[14:15], v[8:11], off
	s_waitcnt vmcnt(15)
	s_nop 1
	v_mov_b64_e32 v[8:9], v[244:245]
	v_mov_b64_e32 v[10:11], v[246:247]
	v_lshl_add_u64 v[12:13], v[128:129], 0, s[10:11]
	v_lshlrev_b32_e32 v14, 16, v8
	v_and_b32_e32 v15, 0xffff0000, v8
	v_lshlrev_b32_e32 v8, 16, v9
	v_and_b32_e32 v9, 0xffff0000, v9
	v_lshlrev_b32_e32 v16, 16, v10
	v_and_b32_e32 v17, 0xffff0000, v10
	v_lshlrev_b32_e32 v10, 16, v11
	v_and_b32_e32 v11, 0xffff0000, v11
	v_pk_mul_f32 v[4:5], v[4:5], v[14:15]
	v_pk_mul_f32 v[6:7], v[6:7], v[8:9]
	v_pk_mul_f32 v[8:9], v[0:1], v[16:17]
	v_pk_mul_f32 v[10:11], v[2:3], v[10:11]
	v_cvt_pk_bf16_f32 v0, v4, v5
	v_cvt_pk_bf16_f32 v1, v6, v7
	v_cvt_pk_bf16_f32 v2, v8, v9
	v_cvt_pk_bf16_f32 v3, v10, v11
	global_store_dwordx4 v[12:13], v[0:3], off offset:256
	s_cbranch_vccnz .LBB0_753
	s_and_b64 vcc, exec, s[0:1]
	s_cbranch_vccnz .LBB0_752
	s_barrier
	s_branch .LBB0_752
	s_nop 0
	s_nop 0
	s_nop 0
	s_nop 0
	s_nop 0
	s_nop 0
	s_nop 0
